# gelu of the u tiles applied in the P3 mixer epilogue (consumer) instead of the P2 epilogue; same f32 op sequence, pU holds bf16 pre-activation
# speedup vs baseline: 1.0030x; 1.0030x over previous
; __device__ __forceinline__ float gelu_tanh(float x) { const float u = 1.5957691216f * (x + 0.044715f * x * x * x); return x * __builtin_amdgcn_rcpf(1.f + __expf(-u)); }
; __device__ __forceinline__ void st_bf16x8(bf16_t* p, const f32x4 a, const f32x4 b) { uint4 o; o.x = cvt_pk_bf16(a[0], a[1]); o.y = cvt_pk_bf16(a[2], a[3]); o.z = cvt_pk_bf16(b[0], b[1]); o.w = cvt_pk_bf16(b[2], b[3]); *(uint4*)p = o; }
;     __device__ __forceinline__ void row(const f32x4 (&a)[2][2], int row, int pn, int wc, int fq) const {
;         if (pn < 2 || pn == 4 || pn == 5) {
;             bf16_t* dst = (pn < 2 ? pU : pBG) + (size_t)row * 512 + (pn & 1) * 256 + wc * 32 + 8 * fq;
; #pragma unroll
;             for (int bj = 0; bj < 2; ++bj) { f32x4 v0 = a[bj][0], v1 = a[bj][1];
;                 if (pn < 2) {
; #pragma unroll
;                     for (int j = 0; j < 4; ++j) { v0[j] = gelu_tanh(v0[j]); v1[j] = gelu_tanh(v1[j]); } }
;                 st_bf16x8(dst + bj * HALF, v0, v1); }
.LBB0_224:
	v_cndmask_b32_e64 v128, 0, 1, s[80:81]
	s_and_b32 s61, s4, 0x100
	s_andn2_b64 vcc, exec, s[0:1]
	v_cmp_ne_u32_e64 s[4:5], 1, v128
	s_cbranch_vccnz .LBB0_230
	s_and_b64 vcc, exec, s[4:5]
.LBB0_227:
	s_and_b64 s[0:1], s[80:81], exec
	v_ashrrev_i32_e32 v157, 31, v156
	s_cselect_b32 s1, s31, s49
	s_cselect_b32 s0, s30, s48
	v_lshlrev_b64 v[128:129], 10, v[156:157]
	v_lshl_add_u64 v[128:129], s[0:1], 0, v[128:129]
	s_lshl_b32 s64, s61, 1
	v_lshl_add_u64 v[128:129], v[128:129], 0, s[64:65]
	s_lshl_b32 s64, s91, 1
	v_lshl_add_u64 v[128:129], v[128:129], 0, s[64:65]
	v_lshlrev_b32_e32 v130, 1, v142
	v_mov_b32_e32 v131, v141
	v_lshl_add_u64 v[128:129], v[128:129], 0, v[130:131]
	s_and_b64 vcc, exec, s[4:5]
	v_cvt_pk_bf16_f32 v124, v124, v125
	v_cvt_pk_bf16_f32 v125, v126, v127
	v_cvt_pk_bf16_f32 v126, v120, v121
	v_cvt_pk_bf16_f32 v127, v122, v123
	global_store_dwordx4 v[128:129], v[124:127], off
.LBB0_229:
	v_cvt_pk_bf16_f32 v116, v116, v117
	v_cvt_pk_bf16_f32 v117, v118, v119
	v_cvt_pk_bf16_f32 v118, v112, v113
	s_nop 0
	v_cvt_pk_bf16_f32 v119, v114, v115
	global_store_dwordx4 v[128:129], v[116:119], off offset:256

; __device__ __forceinline__ float gelu_tanh(float x) { const float u = 1.5957691216f * (x + 0.044715f * x * x * x); return x * __builtin_amdgcn_rcpf(1.f + __expf(-u)); }
; __device__ __forceinline__ void st_bf16x8(bf16_t* p, const f32x4 a, const f32x4 b) { uint4 o; o.x = cvt_pk_bf16(a[0], a[1]); o.y = cvt_pk_bf16(a[2], a[3]); o.z = cvt_pk_bf16(b[0], b[1]); o.w = cvt_pk_bf16(b[2], b[3]); *(uint4*)p = o; }
;     __device__ __forceinline__ void row(const f32x4 (&a)[2][2], int row, int pn, int wc, int fq) const {
;         if (pn < 2 || pn == 4 || pn == 5) {
;             bf16_t* dst = (pn < 2 ? pU : pBG) + (size_t)row * 512 + (pn & 1) * 256 + wc * 32 + 8 * fq;
; #pragma unroll
;             for (int bj = 0; bj < 2; ++bj) { f32x4 v0 = a[bj][0], v1 = a[bj][1];
;                 if (pn < 2) {
; #pragma unroll
;                     for (int j = 0; j < 4; ++j) { v0[j] = gelu_tanh(v0[j]); v1[j] = gelu_tanh(v1[j]); } }
;                 st_bf16x8(dst + bj * HALF, v0, v1); }
.LBB0_246:
	s_and_b64 vcc, exec, s[4:5]
.LBB0_248:
	s_and_b64 s[0:1], s[80:81], exec
	v_ashrrev_i32_e32 v121, 31, v120
	s_cselect_b32 s1, s31, s49
	s_cselect_b32 s0, s30, s48
	v_lshlrev_b64 v[112:113], 10, v[120:121]
	v_lshl_add_u64 v[112:113], s[0:1], 0, v[112:113]
	s_lshl_b32 s64, s61, 1
	v_lshl_add_u64 v[112:113], v[112:113], 0, s[64:65]
	s_lshl_b32 s64, s91, 1
	v_lshl_add_u64 v[112:113], v[112:113], 0, s[64:65]
	v_lshlrev_b32_e32 v114, 1, v142
	v_mov_b32_e32 v115, v141
	v_lshl_add_u64 v[112:113], v[112:113], 0, v[114:115]
	s_and_b64 vcc, exec, s[4:5]
	v_cvt_pk_bf16_f32 v108, v108, v109
	v_cvt_pk_bf16_f32 v109, v110, v111
	v_cvt_pk_bf16_f32 v110, v104, v105
	v_cvt_pk_bf16_f32 v111, v106, v107
	global_store_dwordx4 v[112:113], v[108:111], off
.LBB0_250:
	v_cvt_pk_bf16_f32 v100, v100, v101
	v_cvt_pk_bf16_f32 v101, v102, v103
	v_cvt_pk_bf16_f32 v102, v96, v97
	s_nop 0
	v_cvt_pk_bf16_f32 v103, v98, v99
	global_store_dwordx4 v[112:113], v[100:103], off offset:256
	v_or_b32_e32 v104, 32, v156
	s_and_b64 vcc, exec, s[8:9]
	s_mov_b64 s[0:1], -1
	s_cbranch_vccnz .LBB0_233
	s_branch .LBB0_251
.LBB0_261:
	s_and_b64 vcc, exec, s[4:5]
.LBB0_263:
	s_and_b64 s[0:1], s[80:81], exec
	v_ashrrev_i32_e32 v105, 31, v104
	s_cselect_b32 s1, s31, s49
	s_cselect_b32 s0, s30, s48
	v_lshlrev_b64 v[96:97], 10, v[104:105]
	v_lshl_add_u64 v[96:97], s[0:1], 0, v[96:97]
	s_lshl_b32 s64, s61, 1
	v_lshl_add_u64 v[96:97], v[96:97], 0, s[64:65]
	s_lshl_b32 s64, s91, 1
	v_lshl_add_u64 v[96:97], v[96:97], 0, s[64:65]
	v_lshlrev_b32_e32 v98, 1, v142
	v_mov_b32_e32 v99, v141
	v_lshl_add_u64 v[96:97], v[96:97], 0, v[98:99]
	s_and_b64 vcc, exec, s[4:5]
	v_cvt_pk_bf16_f32 v92, v92, v93
	v_cvt_pk_bf16_f32 v93, v94, v95
	v_cvt_pk_bf16_f32 v94, v88, v89
	v_cvt_pk_bf16_f32 v95, v90, v91
	global_store_dwordx4 v[96:97], v[92:95], off
.LBB0_265:
	v_cvt_pk_bf16_f32 v84, v84, v85
	v_cvt_pk_bf16_f32 v85, v86, v87
	v_cvt_pk_bf16_f32 v86, v80, v81
	s_nop 0
	v_cvt_pk_bf16_f32 v87, v82, v83
	global_store_dwordx4 v[96:97], v[84:87], off offset:256
	v_or_b32_e32 v88, 48, v156
	s_and_b64 vcc, exec, s[8:9]
	s_mov_b64 s[0:1], -1
	s_cbranch_vccnz .LBB0_235
	s_branch .LBB0_266
.LBB0_278:
	s_and_b64 vcc, exec, s[4:5]
.LBB0_280:
	s_and_b64 s[0:1], s[80:81], exec
	v_ashrrev_i32_e32 v89, 31, v88
	s_cselect_b32 s1, s31, s49
	s_cselect_b32 s0, s30, s48
	v_lshlrev_b64 v[80:81], 10, v[88:89]
	v_lshl_add_u64 v[80:81], s[0:1], 0, v[80:81]
	s_lshl_b32 s64, s61, 1
	v_lshl_add_u64 v[80:81], v[80:81], 0, s[64:65]
	s_lshl_b32 s64, s91, 1
	v_lshl_add_u64 v[80:81], v[80:81], 0, s[64:65]
	v_lshlrev_b32_e32 v82, 1, v142
	v_mov_b32_e32 v83, v141
	v_lshl_add_u64 v[80:81], v[80:81], 0, v[82:83]
	s_and_b64 vcc, exec, s[4:5]
	v_cvt_pk_bf16_f32 v76, v76, v77
	v_cvt_pk_bf16_f32 v77, v78, v79
	v_cvt_pk_bf16_f32 v78, v72, v73
	v_cvt_pk_bf16_f32 v79, v74, v75
	global_store_dwordx4 v[80:81], v[76:79], off
.LBB0_282:
	v_cvt_pk_bf16_f32 v68, v68, v69
	v_cvt_pk_bf16_f32 v69, v70, v71
	v_cvt_pk_bf16_f32 v70, v64, v65
	s_nop 0
	v_cvt_pk_bf16_f32 v71, v66, v67
	global_store_dwordx4 v[80:81], v[68:71], off offset:256
	s_branch .LBB0_283

; __device__ __forceinline__ float gelu_tanh(float x) { const float u = 1.5957691216f * (x + 0.044715f * x * x * x); return x * __builtin_amdgcn_rcpf(1.f + __expf(-u)); }
; __device__ __forceinline__ void st_bf16x8(bf16_t* p, const f32x4 a, const f32x4 b) { uint4 o; o.x = cvt_pk_bf16(a[0], a[1]); o.y = cvt_pk_bf16(a[2], a[3]); o.z = cvt_pk_bf16(b[0], b[1]); o.w = cvt_pk_bf16(b[2], b[3]); *(uint4*)p = o; }
;     __device__ __forceinline__ void row(const f32x4 (&a)[2][2], int row, int pn, int wc, int fq) const {
;         if (pn < 2 || pn == 4 || pn == 5) {
;             bf16_t* dst = (pn < 2 ? pU : pBG) + (size_t)row * 512 + (pn & 1) * 256 + wc * 32 + 8 * fq;
; #pragma unroll
;             for (int bj = 0; bj < 2; ++bj) { f32x4 v0 = a[bj][0], v1 = a[bj][1];
;                 if (pn < 2) {
; #pragma unroll
;                     for (int j = 0; j < 4; ++j) { v0[j] = gelu_tanh(v0[j]); v1[j] = gelu_tanh(v1[j]); } }
;                 st_bf16x8(dst + bj * HALF, v0, v1); }
.LBB0_302:
	s_and_b64 vcc, exec, s[4:5]
.LBB0_304:
	s_and_b64 s[0:1], s[80:81], exec
	v_ashrrev_i32_e32 v73, 31, v72
	s_cselect_b32 s1, s31, s49
	s_cselect_b32 s0, s30, s48
	v_lshlrev_b64 v[64:65], 10, v[72:73]
	v_lshl_add_u64 v[64:65], s[0:1], 0, v[64:65]
	s_lshl_b32 s64, s61, 1
	v_lshl_add_u64 v[64:65], v[64:65], 0, s[64:65]
	s_lshl_b32 s64, s91, 1
	v_lshl_add_u64 v[64:65], v[64:65], 0, s[64:65]
	v_lshlrev_b32_e32 v66, 1, v142
	v_mov_b32_e32 v67, v141
	v_lshl_add_u64 v[64:65], v[64:65], 0, v[66:67]
	s_and_b64 vcc, exec, s[4:5]
	v_cvt_pk_bf16_f32 v60, v60, v61
	v_cvt_pk_bf16_f32 v61, v62, v63
	v_cvt_pk_bf16_f32 v62, v56, v57
	v_cvt_pk_bf16_f32 v63, v58, v59
	global_store_dwordx4 v[64:65], v[60:63], off
.LBB0_306:
	v_cvt_pk_bf16_f32 v52, v52, v53
	v_cvt_pk_bf16_f32 v53, v54, v55
	v_cvt_pk_bf16_f32 v54, v48, v49
	s_nop 0
	v_cvt_pk_bf16_f32 v55, v50, v51
	global_store_dwordx4 v[64:65], v[52:55], off offset:256
	v_add_u32_e32 v56, 0x90, v156
	s_and_b64 vcc, exec, s[8:9]
	s_mov_b64 s[0:1], -1
	s_cbranch_vccnz .LBB0_286
	s_branch .LBB0_307
.LBB0_318:
	s_and_b64 vcc, exec, s[4:5]
.LBB0_320:
	s_and_b64 s[0:1], s[80:81], exec
	v_ashrrev_i32_e32 v57, 31, v56
	s_cselect_b32 s1, s31, s49
	s_cselect_b32 s0, s30, s48
	v_lshlrev_b64 v[48:49], 10, v[56:57]
	v_lshl_add_u64 v[48:49], s[0:1], 0, v[48:49]
	s_lshl_b32 s64, s61, 1
	v_lshl_add_u64 v[48:49], v[48:49], 0, s[64:65]
	s_lshl_b32 s64, s91, 1
	v_lshl_add_u64 v[48:49], v[48:49], 0, s[64:65]
	v_lshlrev_b32_e32 v50, 1, v142
	v_mov_b32_e32 v51, v141
	v_lshl_add_u64 v[48:49], v[48:49], 0, v[50:51]
	s_and_b64 vcc, exec, s[4:5]
	v_cvt_pk_bf16_f32 v44, v44, v45
	v_cvt_pk_bf16_f32 v45, v46, v47
	v_cvt_pk_bf16_f32 v46, v40, v41
	v_cvt_pk_bf16_f32 v47, v42, v43
	global_store_dwordx4 v[48:49], v[44:47], off
.LBB0_322:
	v_cvt_pk_bf16_f32 v36, v36, v37
	v_cvt_pk_bf16_f32 v37, v38, v39
	v_cvt_pk_bf16_f32 v38, v32, v33
	s_nop 0
	v_cvt_pk_bf16_f32 v39, v34, v35
	global_store_dwordx4 v[48:49], v[36:39], off offset:256
	v_add_u32_e32 v40, 0xa0, v156
	s_and_b64 vcc, exec, s[8:9]
	s_mov_b64 s[0:1], -1
	s_cbranch_vccnz .LBB0_288
	s_branch .LBB0_323
.LBB0_334:
	s_and_b64 vcc, exec, s[4:5]
.LBB0_336:
	s_and_b64 s[0:1], s[80:81], exec
	v_ashrrev_i32_e32 v41, 31, v40
	s_cselect_b32 s1, s31, s49
	s_cselect_b32 s0, s30, s48
	v_lshlrev_b64 v[32:33], 10, v[40:41]
	v_lshl_add_u64 v[32:33], s[0:1], 0, v[32:33]
	s_lshl_b32 s64, s61, 1
	v_lshl_add_u64 v[32:33], v[32:33], 0, s[64:65]
	s_lshl_b32 s64, s91, 1
	v_lshl_add_u64 v[32:33], v[32:33], 0, s[64:65]
	v_lshlrev_b32_e32 v34, 1, v142
	v_mov_b32_e32 v35, v141
	v_lshl_add_u64 v[32:33], v[32:33], 0, v[34:35]
	s_and_b64 vcc, exec, s[4:5]
	v_cvt_pk_bf16_f32 v28, v28, v29
	v_cvt_pk_bf16_f32 v29, v30, v31
	v_cvt_pk_bf16_f32 v30, v24, v25
	v_cvt_pk_bf16_f32 v31, v26, v27
	global_store_dwordx4 v[32:33], v[28:31], off
.LBB0_338:
	v_cvt_pk_bf16_f32 v20, v20, v21
	v_cvt_pk_bf16_f32 v21, v22, v23
	v_cvt_pk_bf16_f32 v22, v16, v17
	s_nop 0
	v_cvt_pk_bf16_f32 v23, v18, v19
	global_store_dwordx4 v[32:33], v[20:23], off offset:256
	v_add_u32_e32 v24, 0xb0, v156
	s_and_b64 vcc, exec, s[8:9]
	s_mov_b64 s[0:1], -1
	s_cbranch_vccnz .LBB0_290
	s_branch .LBB0_339

; __device__ __forceinline__ void unpack8(const uint4 q, float (&f)[8]) { f[0] = bf_lo(q.x); f[1] = bf_hi(q.x); f[2] = bf_lo(q.y); f[3] = bf_hi(q.y); f[4] = bf_lo(q.z); f[5] = bf_hi(q.z); f[6] = bf_lo(q.w); f[7] = bf_hi(q.w); }
; __device__ __forceinline__ void st_bf16x8(bf16_t* p, const f32x4 a, const f32x4 b) { uint4 o; o.x = cvt_pk_bf16(a[0], a[1]); o.y = cvt_pk_bf16(a[2], a[3]); o.z = cvt_pk_bf16(b[0], b[1]); o.w = cvt_pk_bf16(b[2], b[3]); *(uint4*)p = o; }
; __device__ __forceinline__ void mixer_phase(const Params& p, unsigned char* smem) {
;     ...
;         for (int mt = 0; mt < 4; ++mt) { const int t = thalf * 64 + mt * 16 + fr, row = row0 + t; const float bias = p.b_s[head * 128 + t];
; #pragma unroll
;             for (int pp = 0; pp < 2; ++pp) { const int col = head * 64 + pp * 32 + fq * 8; float u[8]; unpack8(*(const uint4*)(pU + (size_t)row * 512 + col), u);
;                 f32x4 o0 = acc[mt][2 * pp] + bias, o1 = acc[mt][2 * pp + 1] + bias;
; #pragma unroll
;                 for (int j = 0; j < 4; ++j) { o0[j] *= u[j]; o1[j] *= u[4 + j]; }
;                 st_bf16x8(mA + (size_t)row * DM + col, o0, o1); } }
.LBB0_445:
	s_or_b64 exec, exec, s[8:9]
	v_mov_b32_e32 v164, 0x3d372713
	v_mov_b32_e32 v166, 0xbfcc422a
	v_mov_b32_e32 v168, 0x3fb8aa3b
	v_or_b32_e32 v108, s13, v64
	v_lshl_or_b32 v90, v87, 6, v100
	v_lshl_add_u64 v[88:89], v[88:89], 2, s[22:23]
	v_ashrrev_i32_e32 v109, 31, v108
	global_load_dword v106, v[88:89], off
	v_lshlrev_b64 v[88:89], 10, v[108:109]
	v_ashrrev_i32_e32 v91, 31, v90
	v_lshl_add_u64 v[92:93], s[30:31], 0, v[88:89]
	v_lshlrev_b64 v[88:89], 1, v[90:91]
	v_lshl_add_u64 v[94:95], v[92:93], 0, v[88:89]
	global_load_dwordx4 v[90:93], v[94:95], off
	s_nop 0
	global_load_dwordx4 v[94:97], v[94:95], off offset:64
	v_or_b32_e32 v110, s13, v102
	v_ashrrev_i32_e32 v111, 31, v110
	v_lshlrev_b64 v[108:109], 11, v[108:109]
	v_lshlrev_b64 v[112:113], 10, v[110:111]
	v_lshl_add_u64 v[108:109], s[0:1], 0, v[108:109]
	v_lshl_add_u64 v[112:113], s[30:31], 0, v[112:113]
	v_lshl_add_u64 v[108:109], v[108:109], 0, v[88:89]
	v_ashrrev_i32_e32 v87, 31, v86
	v_lshl_add_u64 v[112:113], v[112:113], 0, v[88:89]
	v_lshl_add_u64 v[86:87], v[86:87], 0, v[64:65]
	v_lshl_add_u64 v[86:87], v[86:87], 2, s[22:23]
	s_add_i32 s12, s12, s34
	s_add_i32 s10, s10, s11
	s_cmpk_gt_i32 s12, 0xff
	s_waitcnt vmcnt(2)
	v_pk_add_f32 v[50:51], v[50:51], v[106:107] op_sel_hi:[1,0]
	v_pk_add_f32 v[48:49], v[48:49], v[106:107] op_sel_hi:[1,0]
	v_pk_add_f32 v[54:55], v[54:55], v[106:107] op_sel_hi:[1,0]
	v_pk_add_f32 v[52:53], v[52:53], v[106:107] op_sel_hi:[1,0]
	v_pk_add_f32 v[58:59], v[58:59], v[106:107] op_sel_hi:[1,0]
	v_pk_add_f32 v[56:57], v[56:57], v[106:107] op_sel_hi:[1,0]
	v_pk_add_f32 v[62:63], v[62:63], v[106:107] op_sel_hi:[1,0]
	v_pk_add_f32 v[60:61], v[60:61], v[106:107] op_sel_hi:[1,0]
	s_waitcnt vmcnt(1)
	v_lshlrev_b32_e32 v170, 16, v90
	v_and_b32_e32 v171, 0xffff0000, v90
	v_lshlrev_b32_e32 v172, 16, v91
	v_and_b32_e32 v173, 0xffff0000, v91
	v_lshlrev_b32_e32 v174, 16, v92
	v_and_b32_e32 v175, 0xffff0000, v92
	v_lshlrev_b32_e32 v176, 16, v93
	v_and_b32_e32 v177, 0xffff0000, v93
	v_pk_mul_f32 v[178:179], v[170:171], v[164:165] op_sel_hi:[1,0]
	v_pk_mul_f32 v[180:181], v[172:173], v[164:165] op_sel_hi:[1,0]
	v_pk_mul_f32 v[182:183], v[174:175], v[164:165] op_sel_hi:[1,0]
	v_pk_mul_f32 v[184:185], v[176:177], v[164:165] op_sel_hi:[1,0]
	v_pk_mul_f32 v[178:179], v[170:171], v[178:179]
	v_pk_mul_f32 v[180:181], v[172:173], v[180:181]
	v_pk_mul_f32 v[182:183], v[174:175], v[182:183]
	v_pk_mul_f32 v[184:185], v[176:177], v[184:185]
	v_pk_fma_f32 v[178:179], v[170:171], v[178:179], v[170:171]
	v_pk_fma_f32 v[180:181], v[172:173], v[180:181], v[172:173]
	v_pk_fma_f32 v[182:183], v[174:175], v[182:183], v[174:175]
	v_pk_fma_f32 v[184:185], v[176:177], v[184:185], v[176:177]
	v_pk_mul_f32 v[178:179], v[178:179], v[166:167] op_sel_hi:[1,0]
	v_pk_mul_f32 v[180:181], v[180:181], v[166:167] op_sel_hi:[1,0]
	v_pk_mul_f32 v[182:183], v[182:183], v[166:167] op_sel_hi:[1,0]
	v_pk_mul_f32 v[184:185], v[184:185], v[166:167] op_sel_hi:[1,0]
	v_pk_mul_f32 v[178:179], v[178:179], v[168:169] op_sel_hi:[1,0]
	v_pk_mul_f32 v[180:181], v[180:181], v[168:169] op_sel_hi:[1,0]
	v_pk_mul_f32 v[182:183], v[182:183], v[168:169] op_sel_hi:[1,0]
	v_pk_mul_f32 v[184:185], v[184:185], v[168:169] op_sel_hi:[1,0]
	v_exp_f32_e32 v178, v178
	v_exp_f32_e32 v179, v179
	v_exp_f32_e32 v180, v180
	v_exp_f32_e32 v181, v181
	v_exp_f32_e32 v182, v182
	v_exp_f32_e32 v183, v183
	v_exp_f32_e32 v184, v184
	v_exp_f32_e32 v185, v185
	v_pk_add_f32 v[178:179], v[178:179], 1.0 op_sel_hi:[1,0]
	v_pk_add_f32 v[180:181], v[180:181], 1.0 op_sel_hi:[1,0]
	v_pk_add_f32 v[182:183], v[182:183], 1.0 op_sel_hi:[1,0]
	v_pk_add_f32 v[184:185], v[184:185], 1.0 op_sel_hi:[1,0]
	v_rcp_f32_e32 v178, v178
	v_rcp_f32_e32 v179, v179
	v_rcp_f32_e32 v180, v180
	v_rcp_f32_e32 v181, v181
	v_rcp_f32_e32 v182, v182
	v_rcp_f32_e32 v183, v183
	v_rcp_f32_e32 v184, v184
	v_rcp_f32_e32 v185, v185
	v_pk_mul_f32 v[170:171], v[170:171], v[178:179]
	v_pk_mul_f32 v[172:173], v[172:173], v[180:181]
	v_pk_mul_f32 v[174:175], v[174:175], v[182:183]
	v_pk_mul_f32 v[176:177], v[176:177], v[184:185]
	v_mul_f32_e32 v48, v48, v170
	v_mul_f32_e32 v49, v49, v171
	v_mul_f32_e32 v50, v50, v172
	v_mul_f32_e32 v51, v51, v173
	s_waitcnt vmcnt(0)
	v_lshlrev_b32_e32 v188, 16, v95
	v_and_b32_e32 v189, 0xffff0000, v95
	v_lshlrev_b32_e32 v192, 16, v97
	v_and_b32_e32 v193, 0xffff0000, v97
	v_mul_f32_e32 v52, v52, v174
	v_mul_f32_e32 v53, v53, v175
	v_mul_f32_e32 v54, v54, v176
	v_mul_f32_e32 v55, v55, v177
	v_cvt_pk_bf16_f32 v48, v48, v49
	v_cvt_pk_bf16_f32 v49, v50, v51
	v_cvt_pk_bf16_f32 v50, v52, v53
	v_cvt_pk_bf16_f32 v51, v54, v55
	global_store_dwordx4 v[108:109], v[48:51], off
	v_lshlrev_b32_e32 v186, 16, v94
	v_and_b32_e32 v187, 0xffff0000, v94
	v_lshlrev_b32_e32 v190, 16, v96
	v_and_b32_e32 v191, 0xffff0000, v96
	v_pk_mul_f32 v[194:195], v[186:187], v[164:165] op_sel_hi:[1,0]
	v_pk_mul_f32 v[196:197], v[188:189], v[164:165] op_sel_hi:[1,0]
	v_pk_mul_f32 v[198:199], v[190:191], v[164:165] op_sel_hi:[1,0]
	v_pk_mul_f32 v[200:201], v[192:193], v[164:165] op_sel_hi:[1,0]
	v_pk_mul_f32 v[194:195], v[186:187], v[194:195]
	v_pk_mul_f32 v[196:197], v[188:189], v[196:197]
	v_pk_mul_f32 v[198:199], v[190:191], v[198:199]
	v_pk_mul_f32 v[200:201], v[192:193], v[200:201]
	v_pk_fma_f32 v[194:195], v[186:187], v[194:195], v[186:187]
	v_pk_fma_f32 v[196:197], v[188:189], v[196:197], v[188:189]
	v_pk_fma_f32 v[198:199], v[190:191], v[198:199], v[190:191]
	v_pk_fma_f32 v[200:201], v[192:193], v[200:201], v[192:193]
	v_pk_mul_f32 v[194:195], v[194:195], v[166:167] op_sel_hi:[1,0]
	v_pk_mul_f32 v[196:197], v[196:197], v[166:167] op_sel_hi:[1,0]
; __device__ __forceinline__ void unpack8(const uint4 q, float (&f)[8]) { f[0] = bf_lo(q.x); f[1] = bf_hi(q.x); f[2] = bf_lo(q.y); f[3] = bf_hi(q.y); f[4] = bf_lo(q.z); f[5] = bf_hi(q.z); f[6] = bf_lo(q.w); f[7] = bf_hi(q.w); }
; __device__ __forceinline__ void st_bf16x8(bf16_t* p, const f32x4 a, const f32x4 b) { uint4 o; o.x = cvt_pk_bf16(a[0], a[1]); o.y = cvt_pk_bf16(a[2], a[3]); o.z = cvt_pk_bf16(b[0], b[1]); o.w = cvt_pk_bf16(b[2], b[3]); *(uint4*)p = o; }
; __device__ __forceinline__ void mixer_phase(const Params& p, unsigned char* smem) {
;     ...
;         for (int mt = 0; mt < 4; ++mt) { const int t = thalf * 64 + mt * 16 + fr, row = row0 + t; const float bias = p.b_s[head * 128 + t];
; #pragma unroll
;             for (int pp = 0; pp < 2; ++pp) { const int col = head * 64 + pp * 32 + fq * 8; float u[8]; unpack8(*(const uint4*)(pU + (size_t)row * 512 + col), u);
;                 f32x4 o0 = acc[mt][2 * pp] + bias, o1 = acc[mt][2 * pp + 1] + bias;
; #pragma unroll
;                 for (int j = 0; j < 4; ++j) { o0[j] *= u[j]; o1[j] *= u[4 + j]; }
;                 st_bf16x8(mA + (size_t)row * DM + col, o0, o1); } }
	v_pk_mul_f32 v[198:199], v[198:199], v[166:167] op_sel_hi:[1,0]
	v_pk_mul_f32 v[200:201], v[200:201], v[166:167] op_sel_hi:[1,0]
	v_pk_mul_f32 v[194:195], v[194:195], v[168:169] op_sel_hi:[1,0]
	v_pk_mul_f32 v[196:197], v[196:197], v[168:169] op_sel_hi:[1,0]
	v_pk_mul_f32 v[198:199], v[198:199], v[168:169] op_sel_hi:[1,0]
	v_pk_mul_f32 v[200:201], v[200:201], v[168:169] op_sel_hi:[1,0]
	v_exp_f32_e32 v194, v194
	v_exp_f32_e32 v195, v195
	v_exp_f32_e32 v196, v196
	v_exp_f32_e32 v197, v197
	v_exp_f32_e32 v198, v198
	v_exp_f32_e32 v199, v199
	v_exp_f32_e32 v200, v200
	v_exp_f32_e32 v201, v201
	v_pk_add_f32 v[194:195], v[194:195], 1.0 op_sel_hi:[1,0]
	v_pk_add_f32 v[196:197], v[196:197], 1.0 op_sel_hi:[1,0]
	v_pk_add_f32 v[198:199], v[198:199], 1.0 op_sel_hi:[1,0]
	v_pk_add_f32 v[200:201], v[200:201], 1.0 op_sel_hi:[1,0]
	v_rcp_f32_e32 v194, v194
	v_rcp_f32_e32 v195, v195
	v_rcp_f32_e32 v196, v196
	v_rcp_f32_e32 v197, v197
	v_rcp_f32_e32 v198, v198
	v_rcp_f32_e32 v199, v199
	v_rcp_f32_e32 v200, v200
	v_rcp_f32_e32 v201, v201
	v_pk_mul_f32 v[186:187], v[186:187], v[194:195]
	v_pk_mul_f32 v[188:189], v[188:189], v[196:197]
	v_pk_mul_f32 v[190:191], v[190:191], v[198:199]
	v_pk_mul_f32 v[192:193], v[192:193], v[200:201]
	global_load_dwordx4 v[48:51], v[112:113], off
	v_mul_f32_e32 v53, v59, v189
	v_mul_f32_e32 v55, v63, v193
	v_mul_f32_e32 v56, v56, v186
	v_mul_f32_e32 v60, v60, v190
	v_mul_f32_e32 v57, v57, v187
	v_mul_f32_e32 v61, v61, v191
	v_mul_f32_e32 v58, v58, v188
	v_mul_f32_e32 v62, v62, v192
	v_cvt_pk_bf16_f32 v52, v56, v57
	v_cvt_pk_bf16_f32 v53, v58, v53
	v_cvt_pk_bf16_f32 v54, v60, v61
	v_cvt_pk_bf16_f32 v55, v62, v55
	global_store_dwordx4 v[108:109], v[52:55], off offset:64
	global_load_dword v56, v[86:87], off offset:64
	s_nop 0
	global_load_dwordx4 v[52:55], v[112:113], off offset:64
	v_or_b32_e32 v58, s13, v103
	v_ashrrev_i32_e32 v59, 31, v58
	v_lshlrev_b64 v[60:61], 11, v[110:111]
	v_lshlrev_b64 v[62:63], 10, v[58:59]
	v_lshl_add_u64 v[60:61], s[0:1], 0, v[60:61]
	v_lshl_add_u64 v[62:63], s[30:31], 0, v[62:63]
	v_lshl_add_u64 v[60:61], v[60:61], 0, v[88:89]
	v_lshl_add_u64 v[62:63], v[62:63], 0, v[88:89]
	s_waitcnt vmcnt(3)
	v_lshlrev_b32_e32 v170, 16, v48
	v_and_b32_e32 v171, 0xffff0000, v48
	v_lshlrev_b32_e32 v172, 16, v49
	v_and_b32_e32 v173, 0xffff0000, v49
	v_lshlrev_b32_e32 v174, 16, v50
	v_and_b32_e32 v175, 0xffff0000, v50
	v_lshlrev_b32_e32 v176, 16, v51
	v_and_b32_e32 v177, 0xffff0000, v51
	v_pk_mul_f32 v[178:179], v[170:171], v[164:165] op_sel_hi:[1,0]
	v_pk_mul_f32 v[180:181], v[172:173], v[164:165] op_sel_hi:[1,0]
	v_pk_mul_f32 v[182:183], v[174:175], v[164:165] op_sel_hi:[1,0]
	v_pk_mul_f32 v[184:185], v[176:177], v[164:165] op_sel_hi:[1,0]
	v_pk_mul_f32 v[178:179], v[170:171], v[178:179]
	v_pk_mul_f32 v[180:181], v[172:173], v[180:181]
	v_pk_mul_f32 v[182:183], v[174:175], v[182:183]
	v_pk_mul_f32 v[184:185], v[176:177], v[184:185]
	v_pk_fma_f32 v[178:179], v[170:171], v[178:179], v[170:171]
	v_pk_fma_f32 v[180:181], v[172:173], v[180:181], v[172:173]
	v_pk_fma_f32 v[182:183], v[174:175], v[182:183], v[174:175]
	v_pk_fma_f32 v[184:185], v[176:177], v[184:185], v[176:177]
	v_pk_mul_f32 v[178:179], v[178:179], v[166:167] op_sel_hi:[1,0]
	v_pk_mul_f32 v[180:181], v[180:181], v[166:167] op_sel_hi:[1,0]
	v_pk_mul_f32 v[182:183], v[182:183], v[166:167] op_sel_hi:[1,0]
	v_pk_mul_f32 v[184:185], v[184:185], v[166:167] op_sel_hi:[1,0]
	v_pk_mul_f32 v[178:179], v[178:179], v[168:169] op_sel_hi:[1,0]
	v_pk_mul_f32 v[180:181], v[180:181], v[168:169] op_sel_hi:[1,0]
	v_pk_mul_f32 v[182:183], v[182:183], v[168:169] op_sel_hi:[1,0]
	v_pk_mul_f32 v[184:185], v[184:185], v[168:169] op_sel_hi:[1,0]
	v_exp_f32_e32 v178, v178
	v_exp_f32_e32 v179, v179
	v_exp_f32_e32 v180, v180
	v_exp_f32_e32 v181, v181
	v_exp_f32_e32 v182, v182
	v_exp_f32_e32 v183, v183
	v_exp_f32_e32 v184, v184
	v_exp_f32_e32 v185, v185
	v_pk_add_f32 v[178:179], v[178:179], 1.0 op_sel_hi:[1,0]
	v_pk_add_f32 v[180:181], v[180:181], 1.0 op_sel_hi:[1,0]
	v_pk_add_f32 v[182:183], v[182:183], 1.0 op_sel_hi:[1,0]
	v_pk_add_f32 v[184:185], v[184:185], 1.0 op_sel_hi:[1,0]
	v_rcp_f32_e32 v178, v178
	v_rcp_f32_e32 v179, v179
	v_rcp_f32_e32 v180, v180
	v_rcp_f32_e32 v181, v181
	v_rcp_f32_e32 v182, v182
	v_rcp_f32_e32 v183, v183
	v_rcp_f32_e32 v184, v184
	v_rcp_f32_e32 v185, v185
	v_pk_mul_f32 v[170:171], v[170:171], v[178:179]
	v_pk_mul_f32 v[172:173], v[172:173], v[180:181]
	v_pk_mul_f32 v[174:175], v[174:175], v[182:183]
	v_pk_mul_f32 v[176:177], v[176:177], v[184:185]
	s_waitcnt vmcnt(1)
	v_pk_add_f32 v[34:35], v[34:35], v[56:57] op_sel_hi:[1,0]
	v_pk_add_f32 v[32:33], v[32:33], v[56:57] op_sel_hi:[1,0]
	v_pk_add_f32 v[42:43], v[42:43], v[56:57] op_sel_hi:[1,0]
	v_pk_add_f32 v[40:41], v[40:41], v[56:57] op_sel_hi:[1,0]
	v_mul_f32_e32 v32, v32, v170
	v_mul_f32_e32 v33, v33, v171
	v_mul_f32_e32 v34, v34, v172
	v_mul_f32_e32 v35, v35, v173
	s_waitcnt vmcnt(0)
; __device__ __forceinline__ void unpack8(const uint4 q, float (&f)[8]) { f[0] = bf_lo(q.x); f[1] = bf_hi(q.x); f[2] = bf_lo(q.y); f[3] = bf_hi(q.y); f[4] = bf_lo(q.z); f[5] = bf_hi(q.z); f[6] = bf_lo(q.w); f[7] = bf_hi(q.w); }
; __device__ __forceinline__ void st_bf16x8(bf16_t* p, const f32x4 a, const f32x4 b) { uint4 o; o.x = cvt_pk_bf16(a[0], a[1]); o.y = cvt_pk_bf16(a[2], a[3]); o.z = cvt_pk_bf16(b[0], b[1]); o.w = cvt_pk_bf16(b[2], b[3]); *(uint4*)p = o; }
; __device__ __forceinline__ void mixer_phase(const Params& p, unsigned char* smem) {
;     ...
;         for (int mt = 0; mt < 4; ++mt) { const int t = thalf * 64 + mt * 16 + fr, row = row0 + t; const float bias = p.b_s[head * 128 + t];
; #pragma unroll
;             for (int pp = 0; pp < 2; ++pp) { const int col = head * 64 + pp * 32 + fq * 8; float u[8]; unpack8(*(const uint4*)(pU + (size_t)row * 512 + col), u);
;                 f32x4 o0 = acc[mt][2 * pp] + bias, o1 = acc[mt][2 * pp + 1] + bias;
; #pragma unroll
;                 for (int j = 0; j < 4; ++j) { o0[j] *= u[j]; o1[j] *= u[4 + j]; }
;                 st_bf16x8(mA + (size_t)row * DM + col, o0, o1); } }
	v_lshlrev_b32_e32 v186, 16, v52
	v_and_b32_e32 v187, 0xffff0000, v52
	v_lshlrev_b32_e32 v188, 16, v53
	v_and_b32_e32 v189, 0xffff0000, v53
	v_pk_add_f32 v[38:39], v[38:39], v[56:57] op_sel_hi:[1,0]
	v_pk_add_f32 v[36:37], v[36:37], v[56:57] op_sel_hi:[1,0]
	v_mul_f32_e32 v40, v40, v174
	v_mul_f32_e32 v41, v41, v175
	v_mul_f32_e32 v42, v42, v176
	v_mul_f32_e32 v43, v43, v177
	v_cvt_pk_bf16_f32 v32, v32, v33
	v_cvt_pk_bf16_f32 v33, v34, v35
	v_cvt_pk_bf16_f32 v34, v40, v41
	v_cvt_pk_bf16_f32 v35, v42, v43
	global_store_dwordx4 v[60:61], v[32:35], off
	v_lshlrev_b32_e32 v190, 16, v54
	v_and_b32_e32 v191, 0xffff0000, v54
	v_lshlrev_b32_e32 v192, 16, v55
	v_and_b32_e32 v193, 0xffff0000, v55
	v_pk_mul_f32 v[194:195], v[186:187], v[164:165] op_sel_hi:[1,0]
	v_pk_mul_f32 v[196:197], v[188:189], v[164:165] op_sel_hi:[1,0]
	v_pk_mul_f32 v[198:199], v[190:191], v[164:165] op_sel_hi:[1,0]
	v_pk_mul_f32 v[200:201], v[192:193], v[164:165] op_sel_hi:[1,0]
	v_pk_mul_f32 v[194:195], v[186:187], v[194:195]
	v_pk_mul_f32 v[196:197], v[188:189], v[196:197]
	v_pk_mul_f32 v[198:199], v[190:191], v[198:199]
	v_pk_mul_f32 v[200:201], v[192:193], v[200:201]
	v_pk_fma_f32 v[194:195], v[186:187], v[194:195], v[186:187]
	v_pk_fma_f32 v[196:197], v[188:189], v[196:197], v[188:189]
	v_pk_fma_f32 v[198:199], v[190:191], v[198:199], v[190:191]
	v_pk_fma_f32 v[200:201], v[192:193], v[200:201], v[192:193]
	v_pk_mul_f32 v[194:195], v[194:195], v[166:167] op_sel_hi:[1,0]
	v_pk_mul_f32 v[196:197], v[196:197], v[166:167] op_sel_hi:[1,0]
	v_pk_mul_f32 v[198:199], v[198:199], v[166:167] op_sel_hi:[1,0]
	v_pk_mul_f32 v[200:201], v[200:201], v[166:167] op_sel_hi:[1,0]
	v_pk_mul_f32 v[194:195], v[194:195], v[168:169] op_sel_hi:[1,0]
	v_pk_mul_f32 v[196:197], v[196:197], v[168:169] op_sel_hi:[1,0]
	v_pk_mul_f32 v[198:199], v[198:199], v[168:169] op_sel_hi:[1,0]
	v_pk_mul_f32 v[200:201], v[200:201], v[168:169] op_sel_hi:[1,0]
	v_exp_f32_e32 v194, v194
	v_exp_f32_e32 v195, v195
	v_exp_f32_e32 v196, v196
	v_exp_f32_e32 v197, v197
	v_exp_f32_e32 v198, v198
	v_exp_f32_e32 v199, v199
	v_exp_f32_e32 v200, v200
	v_exp_f32_e32 v201, v201
	v_pk_add_f32 v[194:195], v[194:195], 1.0 op_sel_hi:[1,0]
	v_pk_add_f32 v[196:197], v[196:197], 1.0 op_sel_hi:[1,0]
	v_pk_add_f32 v[198:199], v[198:199], 1.0 op_sel_hi:[1,0]
	v_pk_add_f32 v[200:201], v[200:201], 1.0 op_sel_hi:[1,0]
	v_rcp_f32_e32 v194, v194
	v_rcp_f32_e32 v195, v195
	v_rcp_f32_e32 v196, v196
	v_rcp_f32_e32 v197, v197
	v_rcp_f32_e32 v198, v198
	v_rcp_f32_e32 v199, v199
	v_rcp_f32_e32 v200, v200
	v_rcp_f32_e32 v201, v201
	v_pk_mul_f32 v[186:187], v[186:187], v[194:195]
	v_pk_mul_f32 v[188:189], v[188:189], v[196:197]
	v_pk_mul_f32 v[190:191], v[190:191], v[198:199]
	v_pk_mul_f32 v[192:193], v[192:193], v[200:201]
	v_pk_add_f32 v[46:47], v[46:47], v[56:57] op_sel_hi:[1,0]
	v_pk_add_f32 v[44:45], v[44:45], v[56:57] op_sel_hi:[1,0]
	v_mul_f32_e32 v36, v36, v186
	v_mul_f32_e32 v37, v37, v187
	v_mul_f32_e32 v38, v38, v188
	global_load_dwordx4 v[32:35], v[62:63], off
	v_mul_f32_e32 v39, v39, v189
	v_mul_f32_e32 v44, v44, v190
	v_mul_f32_e32 v45, v45, v191
	v_mul_f32_e32 v46, v46, v192
	v_mul_f32_e32 v40, v47, v193
	v_cvt_pk_bf16_f32 v36, v36, v37
	v_cvt_pk_bf16_f32 v37, v38, v39
	v_cvt_pk_bf16_f32 v38, v44, v45
	v_cvt_pk_bf16_f32 v39, v46, v40
	global_store_dwordx4 v[60:61], v[36:39], off offset:64
	global_load_dword v40, v[86:87], off offset:128
	s_nop 0
	global_load_dwordx4 v[36:39], v[62:63], off offset:64
	v_or_b32_e32 v42, s13, v104
	v_ashrrev_i32_e32 v43, 31, v42
	v_lshlrev_b64 v[44:45], 11, v[58:59]
	v_lshlrev_b64 v[46:47], 10, v[42:43]
	v_lshl_add_u64 v[44:45], s[0:1], 0, v[44:45]
	v_lshl_add_u64 v[46:47], s[30:31], 0, v[46:47]
	v_lshl_add_u64 v[44:45], v[44:45], 0, v[88:89]
	v_lshl_add_u64 v[46:47], v[46:47], 0, v[88:89]
	s_waitcnt vmcnt(3)
	v_lshlrev_b32_e32 v170, 16, v32
	v_and_b32_e32 v171, 0xffff0000, v32
	v_lshlrev_b32_e32 v172, 16, v33
	v_and_b32_e32 v173, 0xffff0000, v33
	v_lshlrev_b32_e32 v174, 16, v34
	v_and_b32_e32 v175, 0xffff0000, v34
	v_lshlrev_b32_e32 v176, 16, v35
	v_and_b32_e32 v177, 0xffff0000, v35
	v_pk_mul_f32 v[178:179], v[170:171], v[164:165] op_sel_hi:[1,0]
	v_pk_mul_f32 v[180:181], v[172:173], v[164:165] op_sel_hi:[1,0]
	v_pk_mul_f32 v[182:183], v[174:175], v[164:165] op_sel_hi:[1,0]
	v_pk_mul_f32 v[184:185], v[176:177], v[164:165] op_sel_hi:[1,0]
	v_pk_mul_f32 v[178:179], v[170:171], v[178:179]
	v_pk_mul_f32 v[180:181], v[172:173], v[180:181]
	v_pk_mul_f32 v[182:183], v[174:175], v[182:183]
	v_pk_mul_f32 v[184:185], v[176:177], v[184:185]
	v_pk_fma_f32 v[178:179], v[170:171], v[178:179], v[170:171]
	v_pk_fma_f32 v[180:181], v[172:173], v[180:181], v[172:173]
	v_pk_fma_f32 v[182:183], v[174:175], v[182:183], v[174:175]
	v_pk_fma_f32 v[184:185], v[176:177], v[184:185], v[176:177]
	v_pk_mul_f32 v[178:179], v[178:179], v[166:167] op_sel_hi:[1,0]
	v_pk_mul_f32 v[180:181], v[180:181], v[166:167] op_sel_hi:[1,0]
	v_pk_mul_f32 v[182:183], v[182:183], v[166:167] op_sel_hi:[1,0]
	v_pk_mul_f32 v[184:185], v[184:185], v[166:167] op_sel_hi:[1,0]
	v_pk_mul_f32 v[178:179], v[178:179], v[168:169] op_sel_hi:[1,0]
	v_pk_mul_f32 v[180:181], v[180:181], v[168:169] op_sel_hi:[1,0]
	v_pk_mul_f32 v[182:183], v[182:183], v[168:169] op_sel_hi:[1,0]
	v_pk_mul_f32 v[184:185], v[184:185], v[168:169] op_sel_hi:[1,0]
	v_exp_f32_e32 v178, v178
	v_exp_f32_e32 v179, v179
	v_exp_f32_e32 v180, v180
	v_exp_f32_e32 v181, v181
	v_exp_f32_e32 v182, v182
	v_exp_f32_e32 v183, v183
	v_exp_f32_e32 v184, v184
	v_exp_f32_e32 v185, v185
	v_pk_add_f32 v[178:179], v[178:179], 1.0 op_sel_hi:[1,0]
	v_pk_add_f32 v[180:181], v[180:181], 1.0 op_sel_hi:[1,0]
	v_pk_add_f32 v[182:183], v[182:183], 1.0 op_sel_hi:[1,0]
	v_pk_add_f32 v[184:185], v[184:185], 1.0 op_sel_hi:[1,0]
	v_rcp_f32_e32 v178, v178
	v_rcp_f32_e32 v179, v179
	v_rcp_f32_e32 v180, v180
	v_rcp_f32_e32 v181, v181
	v_rcp_f32_e32 v182, v182
	v_rcp_f32_e32 v183, v183
	v_rcp_f32_e32 v184, v184
	v_rcp_f32_e32 v185, v185
	v_pk_mul_f32 v[170:171], v[170:171], v[178:179]
	v_pk_mul_f32 v[172:173], v[172:173], v[180:181]
	v_pk_mul_f32 v[174:175], v[174:175], v[182:183]
	v_pk_mul_f32 v[176:177], v[176:177], v[184:185]
	s_waitcnt vmcnt(1)
; __device__ __forceinline__ void unpack8(const uint4 q, float (&f)[8]) { f[0] = bf_lo(q.x); f[1] = bf_hi(q.x); f[2] = bf_lo(q.y); f[3] = bf_hi(q.y); f[4] = bf_lo(q.z); f[5] = bf_hi(q.z); f[6] = bf_lo(q.w); f[7] = bf_hi(q.w); }
; __device__ __forceinline__ void st_bf16x8(bf16_t* p, const f32x4 a, const f32x4 b) { uint4 o; o.x = cvt_pk_bf16(a[0], a[1]); o.y = cvt_pk_bf16(a[2], a[3]); o.z = cvt_pk_bf16(b[0], b[1]); o.w = cvt_pk_bf16(b[2], b[3]); *(uint4*)p = o; }
; __device__ __forceinline__ void mixer_phase(const Params& p, unsigned char* smem) {
;     ...
;         for (int mt = 0; mt < 4; ++mt) { const int t = thalf * 64 + mt * 16 + fr, row = row0 + t; const float bias = p.b_s[head * 128 + t];
; #pragma unroll
;             for (int pp = 0; pp < 2; ++pp) { const int col = head * 64 + pp * 32 + fq * 8; float u[8]; unpack8(*(const uint4*)(pU + (size_t)row * 512 + col), u);
;                 f32x4 o0 = acc[mt][2 * pp] + bias, o1 = acc[mt][2 * pp + 1] + bias;
; #pragma unroll
;                 for (int j = 0; j < 4; ++j) { o0[j] *= u[j]; o1[j] *= u[4 + j]; }
;                 st_bf16x8(mA + (size_t)row * DM + col, o0, o1); } }
	v_pk_add_f32 v[18:19], v[18:19], v[40:41] op_sel_hi:[1,0]
	v_pk_add_f32 v[16:17], v[16:17], v[40:41] op_sel_hi:[1,0]
	v_pk_add_f32 v[26:27], v[26:27], v[40:41] op_sel_hi:[1,0]
	v_pk_add_f32 v[24:25], v[24:25], v[40:41] op_sel_hi:[1,0]
	v_mul_f32_e32 v16, v16, v170
	v_mul_f32_e32 v17, v17, v171
	v_mul_f32_e32 v18, v18, v172
	v_mul_f32_e32 v19, v19, v173
	s_waitcnt vmcnt(0)
	v_lshlrev_b32_e32 v186, 16, v36
	v_and_b32_e32 v187, 0xffff0000, v36
	v_lshlrev_b32_e32 v188, 16, v37
	v_and_b32_e32 v189, 0xffff0000, v37
	v_pk_add_f32 v[22:23], v[22:23], v[40:41] op_sel_hi:[1,0]
	v_pk_add_f32 v[20:21], v[20:21], v[40:41] op_sel_hi:[1,0]
	v_mul_f32_e32 v24, v24, v174
	v_mul_f32_e32 v25, v25, v175
	v_mul_f32_e32 v26, v26, v176
	v_mul_f32_e32 v27, v27, v177
	v_cvt_pk_bf16_f32 v16, v16, v17
	v_cvt_pk_bf16_f32 v17, v18, v19
	v_cvt_pk_bf16_f32 v18, v24, v25
	v_cvt_pk_bf16_f32 v19, v26, v27
	global_store_dwordx4 v[44:45], v[16:19], off
	v_lshlrev_b32_e32 v190, 16, v38
	v_and_b32_e32 v191, 0xffff0000, v38
	v_lshlrev_b32_e32 v192, 16, v39
	v_and_b32_e32 v193, 0xffff0000, v39
	v_pk_mul_f32 v[194:195], v[186:187], v[164:165] op_sel_hi:[1,0]
	v_pk_mul_f32 v[196:197], v[188:189], v[164:165] op_sel_hi:[1,0]
	v_pk_mul_f32 v[198:199], v[190:191], v[164:165] op_sel_hi:[1,0]
	v_pk_mul_f32 v[200:201], v[192:193], v[164:165] op_sel_hi:[1,0]
	v_pk_mul_f32 v[194:195], v[186:187], v[194:195]
	v_pk_mul_f32 v[196:197], v[188:189], v[196:197]
	v_pk_mul_f32 v[198:199], v[190:191], v[198:199]
	v_pk_mul_f32 v[200:201], v[192:193], v[200:201]
	v_pk_fma_f32 v[194:195], v[186:187], v[194:195], v[186:187]
	v_pk_fma_f32 v[196:197], v[188:189], v[196:197], v[188:189]
	v_pk_fma_f32 v[198:199], v[190:191], v[198:199], v[190:191]
	v_pk_fma_f32 v[200:201], v[192:193], v[200:201], v[192:193]
	v_pk_mul_f32 v[194:195], v[194:195], v[166:167] op_sel_hi:[1,0]
	v_pk_mul_f32 v[196:197], v[196:197], v[166:167] op_sel_hi:[1,0]
	v_pk_mul_f32 v[198:199], v[198:199], v[166:167] op_sel_hi:[1,0]
	v_pk_mul_f32 v[200:201], v[200:201], v[166:167] op_sel_hi:[1,0]
	v_pk_mul_f32 v[194:195], v[194:195], v[168:169] op_sel_hi:[1,0]
	v_pk_mul_f32 v[196:197], v[196:197], v[168:169] op_sel_hi:[1,0]
	v_pk_mul_f32 v[198:199], v[198:199], v[168:169] op_sel_hi:[1,0]
	v_pk_mul_f32 v[200:201], v[200:201], v[168:169] op_sel_hi:[1,0]
	v_exp_f32_e32 v194, v194
	v_exp_f32_e32 v195, v195
	v_exp_f32_e32 v196, v196
	v_exp_f32_e32 v197, v197
	v_exp_f32_e32 v198, v198
	v_exp_f32_e32 v199, v199
	v_exp_f32_e32 v200, v200
	v_exp_f32_e32 v201, v201
	v_pk_add_f32 v[194:195], v[194:195], 1.0 op_sel_hi:[1,0]
	v_pk_add_f32 v[196:197], v[196:197], 1.0 op_sel_hi:[1,0]
	v_pk_add_f32 v[198:199], v[198:199], 1.0 op_sel_hi:[1,0]
	v_pk_add_f32 v[200:201], v[200:201], 1.0 op_sel_hi:[1,0]
	v_rcp_f32_e32 v194, v194
	v_rcp_f32_e32 v195, v195
	v_rcp_f32_e32 v196, v196
	v_rcp_f32_e32 v197, v197
	v_rcp_f32_e32 v198, v198
	v_rcp_f32_e32 v199, v199
	v_rcp_f32_e32 v200, v200
	v_rcp_f32_e32 v201, v201
	v_pk_mul_f32 v[186:187], v[186:187], v[194:195]
	v_pk_mul_f32 v[188:189], v[188:189], v[196:197]
	v_pk_mul_f32 v[190:191], v[190:191], v[198:199]
	v_pk_mul_f32 v[192:193], v[192:193], v[200:201]
	v_pk_add_f32 v[30:31], v[30:31], v[40:41] op_sel_hi:[1,0]
	v_pk_add_f32 v[28:29], v[28:29], v[40:41] op_sel_hi:[1,0]
	v_mul_f32_e32 v20, v20, v186
	v_mul_f32_e32 v21, v21, v187
	v_mul_f32_e32 v22, v22, v188
	global_load_dwordx4 v[16:19], v[46:47], off
	v_mul_f32_e32 v23, v23, v189
	v_mul_f32_e32 v28, v28, v190
	v_mul_f32_e32 v29, v29, v191
	v_mul_f32_e32 v30, v30, v192
	v_mul_f32_e32 v24, v31, v193
	v_cvt_pk_bf16_f32 v20, v20, v21
	v_cvt_pk_bf16_f32 v21, v22, v23
	v_cvt_pk_bf16_f32 v22, v28, v29
	v_cvt_pk_bf16_f32 v23, v30, v24
	global_store_dwordx4 v[44:45], v[20:23], off offset:64
	global_load_dword v24, v[86:87], off offset:192
	s_nop 0
	global_load_dwordx4 v[20:23], v[46:47], off offset:64
	v_lshlrev_b64 v[26:27], 11, v[42:43]
	v_lshl_add_u64 v[26:27], s[0:1], 0, v[26:27]
	v_lshl_add_u64 v[26:27], v[26:27], 0, v[88:89]
	s_waitcnt vmcnt(3)
; __device__ __forceinline__ void unpack8(const uint4 q, float (&f)[8]) { f[0] = bf_lo(q.x); f[1] = bf_hi(q.x); f[2] = bf_lo(q.y); f[3] = bf_hi(q.y); f[4] = bf_lo(q.z); f[5] = bf_hi(q.z); f[6] = bf_lo(q.w); f[7] = bf_hi(q.w); }
; __device__ __forceinline__ void st_bf16x8(bf16_t* p, const f32x4 a, const f32x4 b) { uint4 o; o.x = cvt_pk_bf16(a[0], a[1]); o.y = cvt_pk_bf16(a[2], a[3]); o.z = cvt_pk_bf16(b[0], b[1]); o.w = cvt_pk_bf16(b[2], b[3]); *(uint4*)p = o; }
; __device__ __forceinline__ void mixer_phase(const Params& p, unsigned char* smem) {
;     ...
;         for (int mt = 0; mt < 4; ++mt) { const int t = thalf * 64 + mt * 16 + fr, row = row0 + t; const float bias = p.b_s[head * 128 + t];
; #pragma unroll
;             for (int pp = 0; pp < 2; ++pp) { const int col = head * 64 + pp * 32 + fq * 8; float u[8]; unpack8(*(const uint4*)(pU + (size_t)row * 512 + col), u);
;                 f32x4 o0 = acc[mt][2 * pp] + bias, o1 = acc[mt][2 * pp + 1] + bias;
; #pragma unroll
;                 for (int j = 0; j < 4; ++j) { o0[j] *= u[j]; o1[j] *= u[4 + j]; }
;                 st_bf16x8(mA + (size_t)row * DM + col, o0, o1); } }
	v_lshlrev_b32_e32 v170, 16, v16
	v_and_b32_e32 v171, 0xffff0000, v16
	v_lshlrev_b32_e32 v172, 16, v17
	v_and_b32_e32 v173, 0xffff0000, v17
	v_lshlrev_b32_e32 v174, 16, v18
	v_and_b32_e32 v175, 0xffff0000, v18
	v_lshlrev_b32_e32 v176, 16, v19
	v_and_b32_e32 v177, 0xffff0000, v19
	v_pk_mul_f32 v[178:179], v[170:171], v[164:165] op_sel_hi:[1,0]
	v_pk_mul_f32 v[180:181], v[172:173], v[164:165] op_sel_hi:[1,0]
	v_pk_mul_f32 v[182:183], v[174:175], v[164:165] op_sel_hi:[1,0]
	v_pk_mul_f32 v[184:185], v[176:177], v[164:165] op_sel_hi:[1,0]
	v_pk_mul_f32 v[178:179], v[170:171], v[178:179]
	v_pk_mul_f32 v[180:181], v[172:173], v[180:181]
	v_pk_mul_f32 v[182:183], v[174:175], v[182:183]
	v_pk_mul_f32 v[184:185], v[176:177], v[184:185]
	v_pk_fma_f32 v[178:179], v[170:171], v[178:179], v[170:171]
	v_pk_fma_f32 v[180:181], v[172:173], v[180:181], v[172:173]
	v_pk_fma_f32 v[182:183], v[174:175], v[182:183], v[174:175]
	v_pk_fma_f32 v[184:185], v[176:177], v[184:185], v[176:177]
	v_pk_mul_f32 v[178:179], v[178:179], v[166:167] op_sel_hi:[1,0]
	v_pk_mul_f32 v[180:181], v[180:181], v[166:167] op_sel_hi:[1,0]
	v_pk_mul_f32 v[182:183], v[182:183], v[166:167] op_sel_hi:[1,0]
	v_pk_mul_f32 v[184:185], v[184:185], v[166:167] op_sel_hi:[1,0]
	v_pk_mul_f32 v[178:179], v[178:179], v[168:169] op_sel_hi:[1,0]
	v_pk_mul_f32 v[180:181], v[180:181], v[168:169] op_sel_hi:[1,0]
	v_pk_mul_f32 v[182:183], v[182:183], v[168:169] op_sel_hi:[1,0]
	v_pk_mul_f32 v[184:185], v[184:185], v[168:169] op_sel_hi:[1,0]
	v_exp_f32_e32 v178, v178
	v_exp_f32_e32 v179, v179
	v_exp_f32_e32 v180, v180
	v_exp_f32_e32 v181, v181
	v_exp_f32_e32 v182, v182
	v_exp_f32_e32 v183, v183
	v_exp_f32_e32 v184, v184
	v_exp_f32_e32 v185, v185
	v_pk_add_f32 v[178:179], v[178:179], 1.0 op_sel_hi:[1,0]
	v_pk_add_f32 v[180:181], v[180:181], 1.0 op_sel_hi:[1,0]
	v_pk_add_f32 v[182:183], v[182:183], 1.0 op_sel_hi:[1,0]
	v_pk_add_f32 v[184:185], v[184:185], 1.0 op_sel_hi:[1,0]
	v_rcp_f32_e32 v178, v178
	v_rcp_f32_e32 v179, v179
	v_rcp_f32_e32 v180, v180
	v_rcp_f32_e32 v181, v181
	v_rcp_f32_e32 v182, v182
	v_rcp_f32_e32 v183, v183
	v_rcp_f32_e32 v184, v184
	v_rcp_f32_e32 v185, v185
	v_pk_mul_f32 v[170:171], v[170:171], v[178:179]
	v_pk_mul_f32 v[172:173], v[172:173], v[180:181]
	v_pk_mul_f32 v[174:175], v[174:175], v[182:183]
	v_pk_mul_f32 v[176:177], v[176:177], v[184:185]
	s_waitcnt vmcnt(1)
	v_pk_add_f32 v[2:3], v[2:3], v[24:25] op_sel_hi:[1,0]
	v_pk_add_f32 v[0:1], v[0:1], v[24:25] op_sel_hi:[1,0]
	v_pk_add_f32 v[10:11], v[10:11], v[24:25] op_sel_hi:[1,0]
	v_pk_add_f32 v[8:9], v[8:9], v[24:25] op_sel_hi:[1,0]
	s_waitcnt vmcnt(0)
	v_lshlrev_b32_e32 v186, 16, v20
	v_and_b32_e32 v187, 0xffff0000, v20
	v_lshlrev_b32_e32 v188, 16, v21
	v_and_b32_e32 v189, 0xffff0000, v21
	v_pk_add_f32 v[6:7], v[6:7], v[24:25] op_sel_hi:[1,0]
	v_pk_add_f32 v[4:5], v[4:5], v[24:25] op_sel_hi:[1,0]
	v_mul_f32_e32 v0, v0, v170
	v_mul_f32_e32 v1, v1, v171
	v_mul_f32_e32 v2, v2, v172
	v_mul_f32_e32 v3, v3, v173
	v_lshlrev_b32_e32 v190, 16, v22
	v_and_b32_e32 v191, 0xffff0000, v22
	v_lshlrev_b32_e32 v192, 16, v23
	v_and_b32_e32 v193, 0xffff0000, v23
	v_pk_mul_f32 v[194:195], v[186:187], v[164:165] op_sel_hi:[1,0]
	v_pk_mul_f32 v[196:197], v[188:189], v[164:165] op_sel_hi:[1,0]
	v_pk_mul_f32 v[198:199], v[190:191], v[164:165] op_sel_hi:[1,0]
	v_pk_mul_f32 v[200:201], v[192:193], v[164:165] op_sel_hi:[1,0]
	v_pk_mul_f32 v[194:195], v[186:187], v[194:195]
	v_pk_mul_f32 v[196:197], v[188:189], v[196:197]
	v_pk_mul_f32 v[198:199], v[190:191], v[198:199]
	v_pk_mul_f32 v[200:201], v[192:193], v[200:201]
	v_pk_fma_f32 v[194:195], v[186:187], v[194:195], v[186:187]
	v_pk_fma_f32 v[196:197], v[188:189], v[196:197], v[188:189]
	v_pk_fma_f32 v[198:199], v[190:191], v[198:199], v[190:191]
	v_pk_fma_f32 v[200:201], v[192:193], v[200:201], v[192:193]
	v_pk_mul_f32 v[194:195], v[194:195], v[166:167] op_sel_hi:[1,0]
	v_pk_mul_f32 v[196:197], v[196:197], v[166:167] op_sel_hi:[1,0]
	v_pk_mul_f32 v[198:199], v[198:199], v[166:167] op_sel_hi:[1,0]
	v_pk_mul_f32 v[200:201], v[200:201], v[166:167] op_sel_hi:[1,0]
	v_pk_mul_f32 v[194:195], v[194:195], v[168:169] op_sel_hi:[1,0]
	v_pk_mul_f32 v[196:197], v[196:197], v[168:169] op_sel_hi:[1,0]
	v_pk_mul_f32 v[198:199], v[198:199], v[168:169] op_sel_hi:[1,0]
	v_pk_mul_f32 v[200:201], v[200:201], v[168:169] op_sel_hi:[1,0]
	v_exp_f32_e32 v194, v194
	v_exp_f32_e32 v195, v195
	v_exp_f32_e32 v196, v196
	v_exp_f32_e32 v197, v197
	v_exp_f32_e32 v198, v198
	v_exp_f32_e32 v199, v199
	v_exp_f32_e32 v200, v200
	v_exp_f32_e32 v201, v201
	v_pk_add_f32 v[194:195], v[194:195], 1.0 op_sel_hi:[1,0]
	v_pk_add_f32 v[196:197], v[196:197], 1.0 op_sel_hi:[1,0]
	v_pk_add_f32 v[198:199], v[198:199], 1.0 op_sel_hi:[1,0]
	v_pk_add_f32 v[200:201], v[200:201], 1.0 op_sel_hi:[1,0]
	v_rcp_f32_e32 v194, v194
	v_rcp_f32_e32 v195, v195
	v_rcp_f32_e32 v196, v196
	v_rcp_f32_e32 v197, v197
	v_rcp_f32_e32 v198, v198
	v_rcp_f32_e32 v199, v199
	v_rcp_f32_e32 v200, v200
	v_rcp_f32_e32 v201, v201
	v_pk_mul_f32 v[186:187], v[186:187], v[194:195]
	v_pk_mul_f32 v[188:189], v[188:189], v[196:197]
	v_pk_mul_f32 v[190:191], v[190:191], v[198:199]
	v_pk_mul_f32 v[192:193], v[192:193], v[200:201]
	v_pk_add_f32 v[14:15], v[14:15], v[24:25] op_sel_hi:[1,0]
	v_pk_add_f32 v[12:13], v[12:13], v[24:25] op_sel_hi:[1,0]
	v_mul_f32_e32 v8, v8, v174
	v_mul_f32_e32 v9, v9, v175
	v_mul_f32_e32 v10, v10, v176
	v_mul_f32_e32 v11, v11, v177
	v_mul_f32_e32 v4, v4, v186
	v_mul_f32_e32 v5, v5, v187
	v_mul_f32_e32 v6, v6, v188
	v_mul_f32_e32 v7, v7, v189
	v_cvt_pk_bf16_f32 v0, v0, v1
	v_cvt_pk_bf16_f32 v1, v2, v3
	v_cvt_pk_bf16_f32 v2, v8, v9
	v_cvt_pk_bf16_f32 v3, v10, v11
	v_mul_f32_e32 v12, v12, v190
	v_mul_f32_e32 v13, v13, v191
	v_mul_f32_e32 v14, v14, v192
	v_mul_f32_e32 v15, v15, v193
	v_cvt_pk_bf16_f32 v4, v4, v5
	v_cvt_pk_bf16_f32 v5, v6, v7
	v_cvt_pk_bf16_f32 v6, v12, v13
	v_cvt_pk_bf16_f32 v7, v14, v15
	global_store_dwordx4 v[26:27], v[0:3], off
	global_store_dwordx4 v[26:27], v[4:7], off offset:64
	s_barrier
	s_cbranch_scc1 .LBB0_450
